# textually identical grid-barrier instances share one copy (site id in s97, return dispatch), 19 instances removed, to keep the barrier hot path in the instruction cache
# baseline (speedup 1.0000x reference)
.LBB0_432:
	s_waitcnt vmcnt(0)
	s_waitcnt vmcnt(0) lgkmcnt(0)
	s_mov_b32 s97, 3
	s_branch .Lmy_shbar5_entry
.Lmy_shret3:
	v_mov_b32_e32 v21, 0
	v_mbcnt_lo_u32_b32 v0, -1, v0
	v_mbcnt_hi_u32_b32 v0, -1, v0
	v_add_u32_e32 v20, s33, v0
	s_nop 0
	v_readfirstlane_b32 s1, v20
	s_ashr_i32 s2, s1, 6
	v_readlane_b32 s1, v255, 13
	s_add_i32 s1, s2, s1
	s_cmpk_gt_i32 s1, 0x7f
	s_cbranch_scc0 .Lmy_bsk3
	s_barrier
	s_branch .LBB0_489

.LBB0_492:
	s_or_b64 exec, exec, s[4:5]
	s_waitcnt vmcnt(0)
	s_waitcnt lgkmcnt(0)
	s_mov_b32 s97, 4
	s_branch .Lmy_shbar5_entry
.Lmy_shret4:
	s_cmpk_lt_i32 s66, 0x596
	v_mbcnt_lo_u32_b32 v0, -1, v0
	v_mbcnt_hi_u32_b32 v0, -1, v0
	v_add_u32_e32 v10, s33, v0
	s_cselect_b64 s[4:5], -1, 0
	s_cmpk_gt_i32 s66, 0x595
	v_readfirstlane_b32 s3, v10
	s_cbranch_scc1 .LBB0_550
	s_ashr_i32 s1, s66, 31
	s_lshr_b32 s1, s1, 29
	s_add_i32 s1, s66, s1
	s_and_b32 s2, s1, -8
	s_sub_i32 s2, s66, s2
	s_cmp_gt_i32 s2, 5
	s_cbranch_scc0 .LBB0_547
	s_mul_i32 s6, s2, 0xb2
	s_add_i32 s8, s6, 6
	s_cbranch_execz .LBB0_548
	s_branch .LBB0_549

.LBB0_605:
	s_waitcnt vmcnt(0)
	s_waitcnt lgkmcnt(0)
	s_mov_b32 s97, 5
.Lmy_shbar5_entry:
	s_barrier
	s_mov_b64 s[4:5], exec
	v_readlane_b32 s2, v255, 4
	v_readlane_b32 s3, v255, 5
	s_and_b64 s[2:3], s[4:5], s[2:3]
	s_mov_b64 exec, s[2:3]
	s_cbranch_execnz .Lmy_bar5_t0
	s_cmp_eq_u32 s33, 64
	s_cbranch_scc0 .LBB0_657
	s_mov_b64 exec, 1
	buffer_inv sc1
	s_waitcnt vmcnt(0)
	s_branch .LBB0_657

.LBB0_657:
	s_or_b64 exec, exec, s[4:5]
	s_waitcnt lgkmcnt(0)
	v_mov_b32_e32 v0, 0
	s_cmp_eq_u32 s97, 3
	s_cbranch_scc1 .Lmy_shret3
	s_cmp_eq_u32 s97, 4
	s_cbranch_scc1 .Lmy_shret4
	s_cmp_eq_u32 s97, 6
	s_cbranch_scc1 .Lmy_shret6
	s_cmp_eq_u32 s97, 7
	s_cbranch_scc1 .Lmy_shret7
	v_readlane_b32 s4, v255, 16
	v_mbcnt_lo_u32_b32 v0, -1, v0
	v_mbcnt_hi_u32_b32 v0, -1, v0
	v_add_u32_e32 v1, s33, v0
	v_readlane_b32 s5, v255, 17
	s_and_b64 vcc, exec, s[4:5]
	v_readfirstlane_b32 s3, v1
	s_cbranch_vccz .LBB0_660
	s_mov_b64 s[8:9], 0
	s_cmpk_gt_u32 s66, 0x12b
	s_mov_b64 s[6:7], 0
	s_cbranch_scc1 .LBB0_661
	s_and_b32 s31, s66, 3
	s_bfe_u32 s4, s66, 0x40002
	s_mov_b32 s1, 64
	s_mov_b64 s[6:7], -1
	s_branch .LBB0_661

.LBB0_733:
	s_waitcnt vmcnt(0)
	s_waitcnt vmcnt(0) lgkmcnt(0)
	s_mov_b32 s97, 6
	s_branch .Lmy_shbar5_entry
.Lmy_shret6:
	v_mov_b32_e32 v33, 0
	v_mbcnt_lo_u32_b32 v0, -1, v0
	v_mbcnt_hi_u32_b32 v0, -1, v0
	v_add_u32_e32 v32, s33, v0
	s_nop 0
	v_readfirstlane_b32 s1, v32
	s_ashr_i32 s2, s1, 6
	v_readlane_b32 s1, v255, 13
	s_add_i32 s1, s2, s1
	s_cmpk_gt_i32 s1, 0x7f
	s_cbranch_scc0 .Lmy_bsk6
	s_barrier
	s_branch .LBB0_790

.LBB0_793:
	v_writelane_b32 v255, s56, 7
	s_nop 1
	v_writelane_b32 v255, s57, 8
	s_or_b64 exec, exec, s[4:5]
	s_waitcnt vmcnt(0)
	s_waitcnt lgkmcnt(0)
	s_mov_b32 s97, 7
	s_branch .Lmy_shbar5_entry
.Lmy_shret7:
	v_readlane_b32 s4, v255, 20
	v_mbcnt_lo_u32_b32 v0, -1, v0
	v_mbcnt_hi_u32_b32 v0, -1, v0
	v_add_u32_e32 v10, s33, v0
	v_readlane_b32 s5, v255, 21
	s_and_b64 vcc, exec, s[4:5]
	v_readfirstlane_b32 s3, v10
	s_cbranch_vccz .LBB0_848
	s_and_b32 s1, s66, 0x7fffffc0
	s_mov_b64 s[6:7], 0
	s_cmpk_lg_i32 s1, 0x400
	s_mov_b64 s[4:5], 0
	s_cbranch_scc1 .LBB0_849
	s_and_b32 s20, s66, 15
	s_bfe_u32 s18, s66, 0x20004
	s_mov_b32 s8, 64
	s_mov_b64 s[4:5], -1
	s_branch .LBB0_849

.LBB0_1066:
	s_waitcnt vmcnt(0)
	s_mov_b32 s97, 9
	s_branch .Lmy_shbar10_entry
.Lmy_shret9:
	v_readlane_b32 s4, v255, 16
	v_mbcnt_lo_u32_b32 v0, -1, v0
	v_mbcnt_hi_u32_b32 v0, -1, v0
	v_add_u32_e32 v1, s33, v0
	v_readlane_b32 s5, v255, 17
	s_and_b64 vcc, exec, s[4:5]
	v_readfirstlane_b32 s3, v1
	s_cbranch_vccz .LBB0_1121
	s_and_b32 s1, s84, 0x7fffffe0
	s_mov_b64 s[12:13], 0
	s_cmpk_lg_i32 s1, 0x100
	s_mov_b64 s[10:11], 0
	s_cbranch_scc1 .LBB0_1122
	s_and_b32 s6, s84, 3
	s_bfe_u32 s4, s84, 0x30002
	s_mov_b32 s8, 64
	s_mov_b64 s[10:11], -1
	s_branch .LBB0_1122

.LBB0_1205:
	s_waitcnt vmcnt(0)
	s_waitcnt vmcnt(0) lgkmcnt(0)
	s_mov_b32 s97, 10

.LBB0_1257:
	s_or_b64 exec, exec, s[4:5]
	s_waitcnt lgkmcnt(0)
	v_mov_b32_e32 v0, 0
	s_cmp_eq_u32 s97, 9
	s_cbranch_scc1 .Lmy_shret9
	s_cmp_eq_u32 s97, 11
	s_cbranch_scc1 .Lmy_shret11
	v_mov_b32_e32 v21, 0
	v_mbcnt_lo_u32_b32 v0, -1, v0
	v_mbcnt_hi_u32_b32 v0, -1, v0
	v_add_u32_e32 v20, s33, v0
	s_nop 0
	v_readfirstlane_b32 s1, v20
	s_ashr_i32 s2, s1, 6
	v_readlane_b32 s1, v255, 13
	s_add_i32 s1, s2, s1
	s_cmpk_gt_i32 s1, 0x7f
	s_cbranch_scc0 .Lmy_bsk9
	s_barrier
	s_branch .LBB0_1262

.LBB0_1265:
	s_or_b64 exec, exec, s[4:5]
	s_waitcnt vmcnt(0)
	s_waitcnt lgkmcnt(0)
	s_mov_b32 s97, 11
	s_branch .Lmy_shbar10_entry
.Lmy_shret11:
	v_readlane_b32 s2, v255, 41
	v_mbcnt_lo_u32_b32 v0, -1, v0
	v_mbcnt_hi_u32_b32 v0, -1, v0
	v_add_u32_e32 v10, s33, v0
	v_readlane_b32 s3, v255, 42
	s_and_b64 vcc, exec, s[2:3]
	v_readfirstlane_b32 s3, v10
	s_cbranch_vccnz .LBB0_1323
	s_ashr_i32 s1, s84, 31
	s_lshr_b32 s1, s1, 29
	s_add_i32 s1, s84, s1
	s_and_b32 s2, s1, -8
	s_sub_i32 s2, s84, s2
	s_cmp_gt_i32 s2, 5
	s_cbranch_scc0 .LBB0_1320
	s_mul_i32 s4, s2, 0xb2
	s_add_i32 s6, s4, 6
	s_cbranch_execz .LBB0_1321
	s_branch .LBB0_1322

.LBB0_1378:
	s_waitcnt vmcnt(0)
	s_waitcnt lgkmcnt(0)
	s_mov_b32 s97, 12
	s_branch .Lmy_shbar16_entry
.Lmy_shret12:
	v_readlane_b32 s4, v255, 16
	v_mbcnt_lo_u32_b32 v0, -1, v0
	v_mbcnt_hi_u32_b32 v0, -1, v0
	v_add_u32_e32 v1, s33, v0
	v_readlane_b32 s5, v255, 17
	s_and_b64 vcc, exec, s[4:5]
	v_readfirstlane_b32 s3, v1
	s_cbranch_vccz .LBB0_1433
	s_mov_b64 s[8:9], 0
	s_cmpk_gt_u32 s84, 0x12b
	s_mov_b64 s[6:7], 0
	s_cbranch_scc1 .LBB0_1434
	s_bfe_u32 s4, s84, 0x40002
	s_and_b32 s35, s84, 3
	s_mov_b32 s1, 64
	s_mov_b64 s[6:7], -1
	s_branch .LBB0_1434

.LBB0_1541:
	s_waitcnt vmcnt(0)
	s_waitcnt vmcnt(0) lgkmcnt(0)
	s_mov_b32 s97, 13
	s_branch .Lmy_shbar16_entry

.LBB0_1601:
	v_writelane_b32 v255, s58, 7
	s_nop 1
	v_writelane_b32 v255, s59, 8
	s_or_b64 exec, exec, s[4:5]
	s_waitcnt vmcnt(0)
	s_waitcnt lgkmcnt(0)
	s_mov_b32 s97, 14
	s_branch .Lmy_shbar16_entry
.Lmy_shret14:
	s_cmpk_lt_i32 s84, 0xc3
	v_mbcnt_lo_u32_b32 v0, -1, v0
	v_mbcnt_hi_u32_b32 v0, -1, v0
	v_add_u32_e32 v10, s33, v0
	s_cselect_b64 s[6:7], -1, 0
	s_cmpk_gt_i32 s84, 0xc2
	v_readfirstlane_b32 s3, v10
	s_cbranch_scc1 .LBB0_1659
	s_ashr_i32 s1, s84, 31
	s_lshr_b32 s1, s1, 29
	s_add_i32 s1, s84, s1
	s_and_b32 s2, s1, -8
	s_sub_i32 s2, s84, s2
	s_cmp_gt_i32 s2, 2
	s_cbranch_scc0 .LBB0_1656
	s_mul_i32 s4, s2, 24
	s_or_b32 s8, s4, 3
	s_cbranch_execz .LBB0_1657
	s_branch .LBB0_1658

.LBB0_2118:
	s_waitcnt vmcnt(0)
	s_mov_b32 s97, 16

.LBB0_2170:
	s_or_b64 exec, exec, s[4:5]
	s_waitcnt lgkmcnt(0)
	v_mov_b32_e32 v0, 0
	s_cmp_eq_u32 s97, 12
	s_cbranch_scc1 .Lmy_shret12
	s_cmp_eq_u32 s97, 13
	s_cbranch_scc1 .Lmy_shret13
	s_cmp_eq_u32 s97, 14
	s_cbranch_scc1 .Lmy_shret14
	s_cmp_eq_u32 s97, 19
	s_cbranch_scc1 .Lmy_shret19
	s_cmp_eq_u32 s97, 20
	s_cbranch_scc1 .Lmy_shret20
	v_readlane_b32 s2, v255, 43
	v_mbcnt_lo_u32_b32 v0, -1, v0
	v_mbcnt_hi_u32_b32 v0, -1, v0
	v_add_u32_e32 v0, s33, v0
	v_readlane_b32 s3, v255, 44
	s_and_b64 vcc, exec, s[2:3]
	v_readfirstlane_b32 s1, v0
	s_cbranch_vccz .Lmy_bsk15
	s_barrier
	s_branch .LBB0_2202

.LBB0_2636:
	s_waitcnt vmcnt(0)
	s_waitcnt vmcnt(0) lgkmcnt(0)
	s_mov_b32 s97, 19
	s_branch .Lmy_shbar16_entry
.Lmy_shret19:
	v_readlane_b32 s4, v255, 16
	v_mbcnt_lo_u32_b32 v0, -1, v0
	v_mbcnt_hi_u32_b32 v0, -1, v0
	v_add_u32_e32 v1, s33, v0
	v_readlane_b32 s5, v255, 17
	s_and_b64 vcc, exec, s[4:5]
	v_readfirstlane_b32 s3, v1
	s_cbranch_vccz .LBB0_2691
	s_and_b32 s1, s84, 0x7fffffe0
	s_mov_b64 s[12:13], 0
	s_cmpk_lg_i32 s1, 0x100
	s_mov_b64 s[8:9], 0
	s_cbranch_scc1 .LBB0_2692
	s_and_b32 s6, s84, 3
	s_bfe_u32 s4, s84, 0x30002
	s_mov_b32 s14, 64
	s_mov_b64 s[8:9], -1
	s_branch .LBB0_2692

.LBB0_2751:
	s_waitcnt vmcnt(0)
	s_waitcnt vmcnt(0) lgkmcnt(0)
	s_mov_b32 s97, 20
	s_branch .Lmy_shbar16_entry

.LBB0_2924:
	s_waitcnt vmcnt(0)
	s_waitcnt lgkmcnt(0)
	s_mov_b32 s97, 22
	s_branch .Lmy_shbar25_entry

.LBB0_3043:
	s_waitcnt vmcnt(0)
	s_waitcnt vmcnt(0) lgkmcnt(0)
	s_mov_b32 s97, 23
	s_branch .Lmy_shbar25_entry

.LBB0_3103:
	v_writelane_b32 v255, s62, 7
	s_nop 1
	v_writelane_b32 v255, s63, 8
	s_or_b64 exec, exec, s[4:5]
	s_waitcnt vmcnt(0)
	s_waitcnt lgkmcnt(0)
	s_mov_b32 s97, 24
	s_branch .Lmy_shbar25_entry
.Lmy_shret24:
	s_cmpk_lt_i32 s84, 0x82
	v_mbcnt_lo_u32_b32 v0, -1, v0
	v_mbcnt_hi_u32_b32 v0, -1, v0
	v_add_u32_e32 v10, s33, v0
	s_cselect_b64 s[6:7], -1, 0
	s_cmpk_gt_i32 s84, 0x81
	v_readfirstlane_b32 s3, v10
	s_cbranch_scc1 .LBB0_3161
	s_ashr_i32 s1, s84, 31
	s_lshr_b32 s1, s1, 29
	s_add_i32 s1, s84, s1
	s_and_b32 s2, s1, -8
	s_sub_i32 s2, s84, s2
	s_cmp_gt_i32 s2, 1
	s_cbranch_scc0 .LBB0_3158
	s_lshl_b32 s4, s2, 4
	s_or_b32 s8, s4, 2
	s_cbranch_execz .LBB0_3159
	s_branch .LBB0_3160

.LBB0_3367:
	s_waitcnt vmcnt(0)
	s_waitcnt lgkmcnt(0)
	s_mov_b32 s97, 25

.LBB0_3419:
	s_or_b64 exec, exec, s[4:5]
	s_waitcnt lgkmcnt(0)
	v_mov_b32_e32 v0, 0
	s_cmp_eq_u32 s97, 22
	s_cbranch_scc1 .Lmy_shret22
	s_cmp_eq_u32 s97, 23
	s_cbranch_scc1 .Lmy_shret23
	s_cmp_eq_u32 s97, 24
	s_cbranch_scc1 .Lmy_shret24
	s_cmp_eq_u32 s97, 27
	s_cbranch_scc1 .Lmy_shret27
	s_cmp_eq_u32 s97, 28
	s_cbranch_scc1 .Lmy_shret28
	s_cmp_eq_u32 s97, 29
	s_cbranch_scc1 .Lmy_shret29
	s_cmp_eq_u32 s97, 30
	s_cbranch_scc1 .Lmy_shret30
	s_cmp_eq_u32 s97, 31
	s_cbranch_scc1 .Lmy_shret31
	v_readlane_b32 s4, v255, 52
	v_mbcnt_lo_u32_b32 v0, -1, v0
	v_mbcnt_hi_u32_b32 v0, -1, v0
	v_add_u32_e32 v1, s33, v0
	v_readlane_b32 s5, v255, 53
	s_and_b64 vcc, exec, s[4:5]
	v_readfirstlane_b32 s3, v1
	s_cbranch_vccz .LBB0_3422
	s_mov_b64 s[6:7], 0
	s_cmpk_gt_u32 s84, 0x313
	s_mov_b64 s[4:5], 0
	s_cbranch_scc1 .LBB0_3423
	s_add_i32 s1, s84, 0xfffffd00
	s_mov_b32 s2, 64
	s_mov_b64 s[4:5], -1
	s_branch .LBB0_3423

.LBB0_3833:
	s_waitcnt vmcnt(0)
	s_waitcnt vmcnt(0)
	s_mov_b32 s97, 27
	s_branch .Lmy_shbar25_entry
.Lmy_shret27:
	v_readlane_b32 s2, v255, 28
	v_mbcnt_lo_u32_b32 v0, -1, v0
	v_mbcnt_hi_u32_b32 v0, -1, v0
	v_add_u32_e32 v10, s33, v0
	v_readlane_b32 s3, v255, 29
	v_mov_b32_e32 v65, 0
	s_andn2_b64 vcc, exec, s[2:3]
	v_readfirstlane_b32 s1, v10
	s_cbranch_vccz .Lmy_bsk28
	s_barrier
	s_branch .LBB0_3896

.LBB0_3896:
	s_waitcnt vmcnt(0)
	s_waitcnt vmcnt(0) lgkmcnt(0)
	s_mov_b32 s97, 28
	s_branch .Lmy_shbar25_entry
.Lmy_shret28:
	v_readlane_b32 s4, v255, 16
	v_mbcnt_lo_u32_b32 v0, -1, v0
	v_mbcnt_hi_u32_b32 v0, -1, v0
	v_add_u32_e32 v1, s33, v0
	v_readlane_b32 s5, v255, 17
	s_and_b64 vcc, exec, s[4:5]
	v_readfirstlane_b32 s3, v1
	s_cbranch_vccz .LBB0_3951
	s_and_b32 s1, s84, 0x7fffffe0
	s_mov_b64 s[10:11], 0
	s_cmpk_lg_i32 s1, 0x100
	s_mov_b64 s[8:9], 0
	s_cbranch_scc1 .LBB0_3952
	s_bfe_u32 s4, s84, 0x30002
	s_and_b32 s6, s84, 3
	s_mov_b32 s12, 64
	s_mov_b64 s[8:9], -1
	s_branch .LBB0_3952

.LBB0_4011:
	s_waitcnt vmcnt(0)
	s_waitcnt vmcnt(0) lgkmcnt(0)
	s_mov_b32 s97, 29
	s_branch .Lmy_shbar25_entry
.Lmy_shret29:
	v_mov_b32_e32 v23, 0
	v_mbcnt_lo_u32_b32 v0, -1, v0
	v_mbcnt_hi_u32_b32 v0, -1, v0
	v_add_u32_e32 v22, s33, v0
	s_nop 0
	v_readfirstlane_b32 s1, v22
	s_ashr_i32 s2, s1, 6
	v_readlane_b32 s1, v255, 13
	s_add_i32 s1, s2, s1
	s_cmpk_gt_i32 s1, 0x7f
	s_cbranch_scc0 .Lmy_bsk30
	s_barrier
	s_branch .LBB0_4068

.LBB0_4071:
	s_or_b64 exec, exec, s[4:5]
	s_waitcnt vmcnt(0)
	s_waitcnt lgkmcnt(0)
	s_mov_b32 s97, 30
	s_branch .Lmy_shbar25_entry

.LBB0_4175:
	s_waitcnt vmcnt(0)
	s_waitcnt lgkmcnt(0)
	s_mov_b32 s97, 31
	s_branch .Lmy_shbar25_entry
.Lmy_shret31:
	v_readlane_b32 s4, v255, 16
	v_mbcnt_lo_u32_b32 v0, -1, v0
	v_mbcnt_hi_u32_b32 v0, -1, v0
	v_add_u32_e32 v1, s33, v0
	v_readlane_b32 s5, v255, 17
	s_and_b64 vcc, exec, s[4:5]
	v_readfirstlane_b32 s3, v1
	s_cbranch_vccz .LBB0_4230
	s_mov_b64 s[8:9], 0
	s_cmpk_gt_u32 s84, 0x12b
	s_mov_b64 s[6:7], 0
	s_cbranch_scc1 .LBB0_4231
	s_and_b32 s35, s84, 3
	s_bfe_u32 s4, s84, 0x40002
	s_mov_b32 s1, 64
	s_mov_b64 s[6:7], -1
	s_branch .LBB0_4231
